# nt hint also on phase 0's once-read f32 weight/table loads (33 loads), on v22
# speedup vs baseline: 1.0087x; 1.0048x over previous
; __device__ __forceinline__ void s5_tables(const Params& P, int g, int part, unsigned char* lds) {
;     f32x2* pw = (f32x2*)lds; f32x2* Chp = (f32x2*)(lds + 67584); f32x2* Cph = (f32x2*)(lds + 83968); f32x2* Bb = (f32x2*)(lds + 100352); f32x2* kf = (f32x2*)(lds + 116736);
;     const int tid = threadIdx.x;
;     {
;         const int dir = tid >> 8, p = (tid >> 2) & 63, q = tid & 3;
;         const double lr = (double)P.lam_re[(dir * NG + g) * 64 + p], li = (double)P.lam_im[(dir * NG + g) * 64 + p], step = exp((double)P.log_step[dir * NG + g]);
;         const double zr = lr * step, th = li * step;
;         for (int e = q; e <= 64; e += 4) { double s, c; sincos_d(th * e, s, c); const double mag = exp(zr * e); pw[(dir * 64 + p) * 66 + e] = (f32x2){(float)(mag * c), (float)(mag * s)}; }
.LBB0_23:
	s_ashr_i32 s42, s0, 2
	v_add_u32_e32 v24, s42, v73
	v_ashrrev_i32_e32 v25, 31, v24
	v_lshl_or_b32 v26, v24, 6, v57
	v_lshl_add_u64 v[24:25], v[24:25], 2, s[52:53]
	global_load_dword v32, v[24:25], off nt
	v_ashrrev_i32_e32 v27, 31, v26
	v_lshlrev_b64 v[24:25], 2, v[26:27]
	v_lshl_add_u64 v[26:27], s[48:49], 0, v[24:25]
	v_lshl_add_u64 v[24:25], s[50:51], 0, v[24:25]
	global_load_dword v26, v[26:27], off nt
	v_writelane_b32 v255, s0, 11
	global_load_dword v27, v[24:25], off nt
	s_mov_b32 s0, 0x44800000
	s_mov_b32 s28, 0xc4866000
	s_mov_b64 s[6:7], 0
	v_mov_b32_e32 v0, v43
	s_waitcnt vmcnt(2)
	v_cvt_f64_f32_e32 v[28:29], v32
	v_mul_f64 v[30:31], v[28:29], s[94:95]
	v_rndne_f64_e32 v[30:31], v[30:31]
	v_fmac_f64_e32 v[28:29], s[96:97], v[30:31]
	v_fmac_f64_e32 v[28:29], s[2:3], v[30:31]
	v_cvt_i32_f64_e32 v33, v[30:31]
	v_fma_f64 v[30:31], s[90:91], v[28:29], v[6:7]
	v_fma_f64 v[30:31], v[28:29], v[30:31], v[8:9]
	v_fma_f64 v[30:31], v[28:29], v[30:31], v[10:11]
	v_fma_f64 v[30:31], v[28:29], v[30:31], v[12:13]
	v_fma_f64 v[30:31], v[28:29], v[30:31], v[14:15]
	v_fma_f64 v[30:31], v[28:29], v[30:31], v[16:17]
	v_fma_f64 v[30:31], v[28:29], v[30:31], v[18:19]
	v_fma_f64 v[30:31], v[28:29], v[30:31], v[20:21]
	v_fma_f64 v[30:31], v[28:29], v[30:31], v[22:23]
	v_fma_f64 v[30:31], v[28:29], v[30:31], 1.0
	v_fma_f64 v[28:29], v[28:29], v[30:31], 1.0
	v_ldexp_f64 v[28:29], v[28:29], v33
	v_cmp_nlt_f32_e32 vcc, s0, v32
	v_cmp_ngt_f32_e64 s[44:45], s28, v32
	s_waitcnt vmcnt(1)
	v_cvt_f64_f32_e32 v[24:25], v26
	v_cndmask_b32_e32 v29, v55, v29, vcc
	s_and_b64 vcc, s[44:45], vcc
	s_waitcnt vmcnt(0)
	v_cvt_f64_f32_e32 v[26:27], v27
	v_cndmask_b32_e64 v29, 0, v29, s[44:45]
	v_cndmask_b32_e32 v28, 0, v28, vcc
	v_mul_f64 v[30:31], v[28:29], v[24:25]
	v_mul_f64 v[28:29], v[28:29], v[26:27]
	v_mov_b32_e32 v32, v72

; __device__ __forceinline__ void s5_tables(const Params& P, int g, int part, unsigned char* lds) {
;     ...
;     for (int i = tid; i < 2048; i += 512) {
;         const int dir = i >> 10, p = (i >> 4) & 63, h = i & 15;
;         const size_t bi = (((size_t)dir * NG + g) * 64 + p) * 16 + h;
;         const f32x2 k = kf[dir * 64 + p]; const float br = P.b_re[bi], bim = P.b_im[bi];
;         Bb[(dir * 64 + p) * 16 + h] = (f32x2){k.x * br - k.y * bim, k.x * bim + k.y * br};
;         const size_t ci = (((size_t)dir * NG + g) * 16 + h) * 64 + p;
;         const f32x2 cv = (f32x2){P.c_re[ci], P.c_im[ci]};
;         Chp[(dir * 16 + h) * 64 + p] = cv; Cph[(dir * 64 + p) * 16 + h] = cv;
;     }
.LBB0_28:
	v_and_b32_e32 v0, 64, v24
	v_lshl_add_u64 v[28:29], v[0:1], 0, s[42:43]
	v_and_b32_e32 v36, 63, v24
	v_lshlrev_b64 v[28:29], 10, v[28:29]
	v_lshl_or_b32 v0, v36, 4, v28
	v_mov_b32_e32 v31, v29
	v_or_b32_e32 v28, v28, v76
	v_or_b32_e32 v30, v0, v75
	v_or_b32_e32 v28, v28, v36
	v_lshlrev_b64 v[30:31], 2, v[30:31]
	v_lshlrev_b64 v[28:29], 2, v[28:29]
	v_lshl_add_u64 v[32:33], s[54:55], 0, v[30:31]
	v_lshl_add_u64 v[30:31], s[56:57], 0, v[30:31]
	v_lshl_add_u64 v[34:35], s[58:59], 0, v[28:29]
	v_lshl_add_u64 v[28:29], s[60:61], 0, v[28:29]
	global_load_dword v0, v[30:31], off nt
	s_nop 0
	global_load_dword v30, v[32:33], off nt
	s_nop 0
	global_load_dword v32, v[34:35], off nt
	global_load_dword v33, v[28:29], off nt
	ds_read_b64 v[28:29], v25
	v_and_b32_e32 v31, 0x400, v27
	v_add_u32_e32 v34, 0x200, v27
	s_movk_i32 s0, 0x5ff
	v_lshlrev_b32_e32 v31, 3, v31
	v_lshlrev_b32_e32 v35, 3, v36
	v_cmp_lt_u32_e32 vcc, s0, v27
	v_mov_b32_e32 v27, v34
	v_add3_u32 v31, v77, v31, v35
	v_add_u32_e32 v25, 0x100, v25
	v_add_u32_e32 v24, 32, v24
	s_or_b64 s[6:7], vcc, s[6:7]
	s_waitcnt vmcnt(3) lgkmcnt(0)
	v_pk_mul_f32 v[34:35], v[28:29], v[0:1] op_sel:[1,0] op_sel_hi:[0,0]
	s_waitcnt vmcnt(2)
	v_pk_fma_f32 v[36:37], v[28:29], v[30:31], v[34:35] neg_lo:[0,0,1] neg_hi:[0,0,1]
	v_pk_fma_f32 v[28:29], v[28:29], v[30:31], v[34:35] op_sel_hi:[1,0,1]
	s_nop 0
	v_mov_b32_e32 v37, v29
	ds_write_b64 v26, v[36:37] offset:16384
	s_waitcnt vmcnt(0)
	ds_write_b64 v31, v[32:33]
	ds_write_b64 v26, v[32:33]
	v_add_u32_e32 v26, 0x1000, v26
	s_andn2_b64 exec, exec, s[6:7]
	s_cbranch_execnz .LBB0_28
	s_or_b64 exec, exec, s[6:7]
	v_readlane_b32 s0, v255, 11
	s_and_b32 s0, s0, 3
	s_cmp_gt_u32 s0, 1
	s_mov_b64 s[6:7], -1
	s_mov_b32 s92, 0x20000
	s_waitcnt lgkmcnt(0)
	s_barrier
	s_cbranch_scc0 .LBB0_39
	s_lshl_b64 s[6:7], s[42:43], 19
	s_cmp_lg_u32 s0, 2
	s_mov_b64 s[44:45], -1
	s_cbranch_scc0 .LBB0_34
	v_lshl_add_u64 v[24:25], v[2:3], 0, s[6:7]
	s_mov_b32 s43, 3
	s_movk_i32 s44, 0xc000
	s_mov_b32 s45, 0
	s_mov_b32 s46, 0

; __device__ __forceinline__ void s5_tables(const Params& P, int g, int part, unsigned char* lds) {
;     ...
;             if (j == 0) { const float dv = P.s5d[g * 16 + h];
; #pragma unroll
;                 for (int k = 0; k < 16; ++k) a[k] += (k == h) ? dv : 0.f; }
.LBB0_54:
	global_load_dword v60, v[24:25], off nt
	v_readlane_b32 s42, v254, 11
	v_readlane_b32 s43, v254, 12
	s_waitcnt vmcnt(0)
	s_nop 0
	v_cndmask_b32_e64 v61, 0, v60, s[42:43]
	v_readlane_b32 s42, v254, 13
	v_readlane_b32 s43, v254, 14
	v_add_f32_e32 v40, v40, v61
	s_nop 0
	v_cndmask_b32_e64 v62, 0, v60, s[42:43]
	v_readlane_b32 s42, v254, 15
	v_readlane_b32 s43, v254, 16
	v_add_f32_e32 v41, v41, v62
	s_nop 0
	v_cndmask_b32_e64 v63, 0, v60, s[42:43]
	v_readlane_b32 s42, v254, 17
	v_readlane_b32 s43, v254, 18
	v_add_f32_e32 v38, v38, v63
	s_nop 0
	v_cndmask_b32_e64 v64, 0, v60, s[42:43]
	v_readlane_b32 s42, v254, 19
	v_readlane_b32 s43, v254, 20
	v_add_f32_e32 v39, v39, v64
	s_nop 0
	v_cndmask_b32_e64 v65, 0, v60, s[42:43]
	v_readlane_b32 s42, v254, 21
	v_readlane_b32 s43, v254, 22
	v_add_f32_e32 v36, v36, v65
	s_nop 0
	v_cndmask_b32_e64 v66, 0, v60, s[42:43]
	v_readlane_b32 s42, v254, 23
	v_readlane_b32 s43, v254, 24
	v_add_f32_e32 v37, v37, v66
	s_nop 0
	v_cndmask_b32_e64 v67, 0, v60, s[42:43]
	v_readlane_b32 s42, v254, 25
	v_readlane_b32 s43, v254, 26
	v_add_f32_e32 v34, v34, v67
	s_nop 0
	v_cndmask_b32_e64 v68, 0, v60, s[42:43]
	v_readlane_b32 s42, v254, 27
	v_readlane_b32 s43, v254, 28
	v_add_f32_e32 v35, v35, v68
	s_nop 0
	v_cndmask_b32_e64 v69, 0, v60, s[42:43]
	v_readlane_b32 s42, v254, 29
	v_readlane_b32 s43, v254, 30
	v_add_f32_e32 v32, v32, v69
	s_nop 0
	v_cndmask_b32_e64 v70, 0, v60, s[42:43]
	v_readlane_b32 s42, v254, 31
	v_readlane_b32 s43, v254, 32
	v_add_f32_e32 v33, v33, v70
	s_nop 0
	v_cndmask_b32_e64 v71, 0, v60, s[42:43]
	v_readlane_b32 s42, v254, 55
	v_readlane_b32 s43, v254, 56
	v_add_f32_e32 v30, v30, v71
	s_nop 0
	v_cndmask_b32_e64 v91, 0, v60, s[42:43]
	v_readlane_b32 s42, v254, 57
	v_readlane_b32 s43, v254, 58
	v_add_f32_e32 v31, v31, v91
	s_nop 0
	v_cndmask_b32_e64 v92, 0, v60, s[42:43]
	v_readlane_b32 s42, v254, 62
	v_readlane_b32 s43, v254, 63
	v_add_f32_e32 v28, v28, v92
	s_nop 0
	v_cndmask_b32_e64 v93, 0, v60, s[42:43]
	v_readlane_b32 s42, v255, 0
	v_readlane_b32 s43, v255, 1
	v_add_f32_e32 v29, v29, v93
	s_nop 0
	v_cndmask_b32_e64 v94, 0, v60, s[42:43]
	v_readlane_b32 s42, v255, 2
	v_readlane_b32 s43, v255, 3
	v_add_f32_e32 v26, v26, v94
	s_nop 0
	v_cndmask_b32_e64 v60, 0, v60, s[42:43]
	v_add_f32_e32 v27, v27, v60
	s_branch .LBB0_44

; __global__ void __launch_bounds__(512, 2) fwd_megakernel(Params Pk) {
;     ...
;             for (int wi = gw; wi < NWI_GU + NWI_GLU + NWI_POOL; wi += NW) {
;                 const float* src; int stride; bf16_t* dst; const float* kg = nullptr; float ns = 1.0f;
;                 if (wi < NWI_GU) conv_addr(j, wi, lane, src, stride, dst, kg);
;                 else if (wi < NWI_GU + NWI_GLU) { const int w2 = wi - NWI_GU, rb = w2 >> 7, k0 = (w2 & 127) * 8, pn = rb >> 2, bj = (rb >> 1) & 1;
;                     src = P.glu_a + (ptrdiff_t)bj * (P.glu_b - P.glu_a) + (size_t)k0 * D + pn * 128 + (rb & 1) * 64 + lane; stride = D; dst = (bf16_t*)(ws + OFF_WGLU) + (size_t)(rb * 64 + lane) * D + k0; }
;                 else { const int w2 = wi - NWI_GU - NWI_GLU, rb = w2 >> 5, k0 = (w2 & 31) * 8, g = rb >> 2, d0 = (rb & 3) * 64;
;                     src = P.pool_w + (size_t)g * 65536 + (size_t)k0 * 256 + d0 + lane; stride = 256; dst = (bf16_t*)(ws + OFF_WPOOL) + (size_t)(rb * 64 + lane) * 256 + k0; ns = P.pool_scale[g * 256 + d0 + lane]; }
.LBB0_69:
	s_movk_i32 s14, 0x2bff
	v_cmp_lt_i32_e32 vcc, s14, v49
	s_and_saveexec_b64 s[14:15], vcc
	s_xor_b64 s[14:15], exec, s[14:15]
	s_cbranch_execz .LBB0_75
	s_movk_i32 s16, 0x3bff
	v_cmp_lt_u32_e32 vcc, s16, v49
	s_and_saveexec_b64 s[16:17], vcc
	s_xor_b64 s[16:17], exec, s[16:17]
	s_cbranch_execz .LBB0_72
	v_add_u32_e32 v0, 0xffffc400, v49
	v_lshrrev_b32_e32 v0, 7, v0
	v_and_b32_e32 v3, 0xc0, v12
	s_waitcnt lgkmcnt(0)
	v_lshlrev_b64 v[4:5], 18, v[0:1]
	v_lshlrev_b32_e32 v0, 8, v0
	v_or3_b32 v0, v0, v3, v56
	v_lshl_add_u64 v[6:7], v[0:1], 2, s[42:43]
	global_load_dword v0, v[6:7], off nt
	v_and_b32_e32 v10, 0xf8, v13
	v_lshl_add_u64 v[4:5], s[40:41], 0, v[4:5]
	v_lshlrev_b32_e32 v6, 10, v10
	v_mov_b32_e32 v7, v1
	v_lshl_add_u64 v[4:5], v[4:5], 0, v[6:7]
	v_lshlrev_b32_e32 v6, 2, v3
	v_lshl_add_u64 v[4:5], v[4:5], 0, v[6:7]
	v_mov_b32_e32 v3, v1
	v_lshl_add_u64 v[8:9], v[4:5], 0, v[2:3]
	v_and_or_b32 v4, v12, s21, v56
	v_mov_b32_e32 v5, v1
	v_lshlrev_b64 v[4:5], 9, v[4:5]
	v_lshl_add_u64 v[4:5], s[6:7], 0, v[4:5]
	v_lshlrev_b32_e32 v6, 1, v10
	v_lshl_add_u64 v[4:5], v[4:5], 0, v[6:7]

; __device__ __forceinline__ void conv_load(const float* src, int stride, float (&v)[8]) {
; #pragma unroll
;     for (int j = 0; j < 8; ++j) v[j] = src[(size_t)j * stride];
; }
; __device__ __forceinline__ void conv_store(bf16_t* dst, const float (&v)[8], const float* kgain, float nscale) {
;     float g[8];
; #pragma unroll
;     for (int j = 0; j < 8; ++j) g[j] = kgain ? kgain[j] * nscale : nscale;
; __global__ void __launch_bounds__(512, 2) fwd_megakernel(Params Pk) {
;     ...
;                 float v[8]; conv_load(src, stride, v); conv_store(dst, v, kg, ns);
.LBB0_77:
	s_or_b64 exec, exec, s[14:15]
	v_lshlrev_b64 v[10:11], 2, v[10:11]
	v_lshl_add_u64 v[16:17], v[8:9], 0, v[10:11]
	v_lshl_add_u64 v[18:19], v[16:17], 0, v[10:11]
	v_lshl_add_u64 v[20:21], v[18:19], 0, v[10:11]
	v_lshl_add_u64 v[22:23], v[20:21], 0, v[10:11]
	v_lshl_add_u64 v[24:25], v[22:23], 0, v[10:11]
	v_lshl_add_u64 v[26:27], v[24:25], 0, v[10:11]
	v_lshl_add_u64 v[28:29], v[26:27], 0, v[10:11]
	global_load_dword v15, v[8:9], off nt
	s_nop 0
	global_load_dword v16, v[16:17], off nt
	s_nop 0
	global_load_dword v11, v[18:19], off nt
	global_load_dword v14, v[20:21], off nt
	global_load_dword v9, v[22:23], off nt
	global_load_dword v10, v[24:25], off nt
	global_load_dword v3, v[26:27], off nt
	global_load_dword v8, v[28:29], off nt
	v_cmp_ne_u64_e32 vcc, 0, v[6:7]
	s_waitcnt vmcnt(8)
	v_mov_b32_e32 v17, v0
	s_and_saveexec_b64 s[14:15], vcc
	s_cbranch_execnz .LBB0_85
	s_or_b64 exec, exec, s[14:15]
	v_mov_b32_e32 v18, v0
	s_and_saveexec_b64 s[14:15], vcc
	s_cbranch_execnz .LBB0_86

; __device__ __forceinline__ void conv_store(bf16_t* dst, const float (&v)[8], const float* kgain, float nscale) {
;     float g[8];
; #pragma unroll
;     for (int j = 0; j < 8; ++j) g[j] = kgain ? kgain[j] * nscale : nscale;
.LBB0_85:
	global_load_dword v17, v[6:7], off nt
	s_waitcnt vmcnt(0)
	v_mul_f32_e32 v17, v0, v17
	s_or_b64 exec, exec, s[14:15]
	v_mov_b32_e32 v18, v0
	s_and_saveexec_b64 s[14:15], vcc
	s_cbranch_execz .LBB0_79
.LBB0_86:
	global_load_dword v18, v[6:7], off offset:4 nt
	s_waitcnt vmcnt(0)
	v_mul_f32_e32 v18, v0, v18
	s_or_b64 exec, exec, s[14:15]
	v_mov_b32_e32 v19, v0
	s_and_saveexec_b64 s[14:15], vcc
	s_cbranch_execz .LBB0_80
.LBB0_87:
	global_load_dword v19, v[6:7], off offset:8 nt
	s_waitcnt vmcnt(0)
	v_mul_f32_e32 v19, v0, v19
	s_or_b64 exec, exec, s[14:15]
	v_mov_b32_e32 v20, v0
	s_and_saveexec_b64 s[14:15], vcc
	s_cbranch_execz .LBB0_81
.LBB0_88:
	global_load_dword v20, v[6:7], off offset:12 nt
	s_waitcnt vmcnt(0)
	v_mul_f32_e32 v20, v0, v20
	s_or_b64 exec, exec, s[14:15]
	v_mov_b32_e32 v21, v0
	s_and_saveexec_b64 s[14:15], vcc
	s_cbranch_execz .LBB0_82
.LBB0_89:
	global_load_dword v21, v[6:7], off offset:16 nt
	s_waitcnt vmcnt(0)
	v_mul_f32_e32 v21, v0, v21
	s_or_b64 exec, exec, s[14:15]
	v_mov_b32_e32 v22, v0
	s_and_saveexec_b64 s[14:15], vcc
	s_cbranch_execz .LBB0_83
.LBB0_90:
	global_load_dword v22, v[6:7], off offset:20 nt
	s_waitcnt vmcnt(0)
	v_mul_f32_e32 v22, v0, v22
	s_or_b64 exec, exec, s[14:15]
	v_mov_b32_e32 v23, v0
	s_and_saveexec_b64 s[14:15], vcc
	s_cbranch_execz .LBB0_84
.LBB0_91:
	global_load_dword v23, v[6:7], off offset:24 nt
	s_waitcnt vmcnt(0)
	v_mul_f32_e32 v23, v0, v23
	s_or_b64 exec, exec, s[14:15]
	s_and_saveexec_b64 s[14:15], vcc
	s_cbranch_execz .LBB0_68
.LBB0_92:
	global_load_dword v6, v[6:7], off offset:28 nt
	s_waitcnt vmcnt(0)
	v_mul_f32_e32 v0, v0, v6
	s_branch .LBB0_68

; __device__ __forceinline__ void s5_tables(const Params& P, int g, int part, unsigned char* lds) {
;     ...
;         const int dir = tid >> 8, p = (tid >> 2) & 63, q = tid & 3;
;         const double lr = (double)P.lam_re[(dir * NG + g) * 64 + p], li = (double)P.lam_im[(dir * NG + g) * 64 + p], step = exp((double)P.log_step[dir * NG + g]);
;         const double zr = lr * step, th = li * step;
;         for (int e = q; e <= 64; e += 4) { double s, c; sincos_d(th * e, s, c); const double mag = exp(zr * e); pw[(dir * 64 + p) * 66 + e] = (f32x2){(float)(mag * c), (float)(mag * s)}; }
.LBB0_97:
	s_ashr_i32 s42, s0, 2
	v_add_u32_e32 v22, s42, v73
	v_ashrrev_i32_e32 v23, 31, v22
	v_lshl_or_b32 v24, v22, 6, v57
	v_lshl_add_u64 v[22:23], v[22:23], 2, s[52:53]
	global_load_dword v31, v[22:23], off nt
	v_ashrrev_i32_e32 v25, 31, v24
	v_lshlrev_b64 v[22:23], 2, v[24:25]
	v_lshl_add_u64 v[24:25], s[48:49], 0, v[22:23]
	v_lshl_add_u64 v[22:23], s[50:51], 0, v[22:23]
	global_load_dword v24, v[24:25], off nt
	v_writelane_b32 v254, s0, 61
	global_load_dword v25, v[22:23], off nt
	s_mov_b32 s0, 0x44800000
	s_mov_b32 s28, 0xc4866000
	s_mov_b64 s[6:7], 0
	v_mov_b32_e32 v30, v40
	s_waitcnt vmcnt(2)
	v_cvt_f64_f32_e32 v[26:27], v31
	v_mul_f64 v[28:29], v[26:27], s[64:65]
	v_rndne_f64_e32 v[28:29], v[28:29]
	v_fmac_f64_e32 v[26:27], s[66:67], v[28:29]
	v_fmac_f64_e32 v[26:27], s[68:69], v[28:29]
	v_cvt_i32_f64_e32 v32, v[28:29]
	v_fma_f64 v[28:29], s[4:5], v[26:27], v[4:5]
	v_fma_f64 v[28:29], v[26:27], v[28:29], v[6:7]
	v_fma_f64 v[28:29], v[26:27], v[28:29], v[8:9]
	v_fma_f64 v[28:29], v[26:27], v[28:29], v[10:11]
	v_fma_f64 v[28:29], v[26:27], v[28:29], v[12:13]
	v_fma_f64 v[28:29], v[26:27], v[28:29], v[14:15]
	v_fma_f64 v[28:29], v[26:27], v[28:29], v[16:17]
	v_fma_f64 v[28:29], v[26:27], v[28:29], v[18:19]
	v_fma_f64 v[28:29], v[26:27], v[28:29], v[20:21]
	v_fma_f64 v[28:29], v[26:27], v[28:29], 1.0
	v_fma_f64 v[26:27], v[26:27], v[28:29], 1.0
	v_ldexp_f64 v[26:27], v[26:27], v32
	v_cmp_nlt_f32_e32 vcc, s0, v31
	v_cmp_ngt_f32_e64 s[44:45], s28, v31
	s_waitcnt vmcnt(1)
	v_cvt_f64_f32_e32 v[22:23], v24
	v_cndmask_b32_e32 v27, v46, v27, vcc
	s_and_b64 vcc, s[44:45], vcc
	s_waitcnt vmcnt(0)
	v_cvt_f64_f32_e32 v[24:25], v25
	v_cndmask_b32_e64 v27, 0, v27, s[44:45]
	v_cndmask_b32_e32 v26, 0, v26, vcc
	v_mul_f64 v[28:29], v[26:27], v[22:23]
	v_mul_f64 v[26:27], v[26:27], v[24:25]
	v_mov_b32_e32 v31, v72

; __device__ __forceinline__ void s5_tables(const Params& P, int g, int part, unsigned char* lds) {
;     ...
;     for (int i = tid; i < 2048; i += 512) {
;         const int dir = i >> 10, p = (i >> 4) & 63, h = i & 15;
;         const size_t bi = (((size_t)dir * NG + g) * 64 + p) * 16 + h;
;         const f32x2 k = kf[dir * 64 + p]; const float br = P.b_re[bi], bim = P.b_im[bi];
;         Bb[(dir * 64 + p) * 16 + h] = (f32x2){k.x * br - k.y * bim, k.x * bim + k.y * br};
;         const size_t ci = (((size_t)dir * NG + g) * 16 + h) * 64 + p;
;         const f32x2 cv = (f32x2){P.c_re[ci], P.c_im[ci]};
;         Chp[(dir * 16 + h) * 64 + p] = cv; Cph[(dir * 64 + p) * 16 + h] = cv;
;     }
.LBB0_102:
	v_and_b32_e32 v48, 64, v22
	v_lshl_add_u64 v[26:27], v[48:49], 0, s[42:43]
	v_and_b32_e32 v34, 63, v22
	v_lshlrev_b64 v[26:27], 10, v[26:27]
	v_lshl_or_b32 v28, v34, 4, v26
	v_or_b32_e32 v26, v26, v76
	v_mov_b32_e32 v29, v27
	v_or_b32_e32 v28, v28, v75
	v_or_b32_e32 v26, v26, v34
	v_lshlrev_b64 v[28:29], 2, v[28:29]
	v_lshlrev_b64 v[26:27], 2, v[26:27]
	v_lshl_add_u64 v[30:31], s[54:55], 0, v[28:29]
	v_lshl_add_u64 v[28:29], s[56:57], 0, v[28:29]
	v_lshl_add_u64 v[32:33], s[58:59], 0, v[26:27]
	v_lshl_add_u64 v[26:27], s[60:61], 0, v[26:27]
	global_load_dword v28, v[28:29], off nt
	s_nop 0
	global_load_dword v30, v[30:31], off nt
	s_nop 0
	global_load_dword v32, v[32:33], off nt
	s_nop 0
	global_load_dword v33, v[26:27], off nt
	ds_read_b64 v[26:27], v23
	v_and_b32_e32 v29, 0x400, v25
	v_add_u32_e32 v31, 0x200, v25
	s_movk_i32 s0, 0x5ff
	v_lshlrev_b32_e32 v29, 3, v29
	v_lshlrev_b32_e32 v34, 3, v34
	v_cmp_lt_u32_e32 vcc, s0, v25
	v_mov_b32_e32 v25, v31
	v_add3_u32 v31, v77, v29, v34
	v_add_u32_e32 v23, 0x100, v23
	v_add_u32_e32 v22, 32, v22
	s_or_b64 s[6:7], vcc, s[6:7]
	s_waitcnt vmcnt(3) lgkmcnt(0)
	v_pk_mul_f32 v[28:29], v[26:27], v[28:29] op_sel:[1,0] op_sel_hi:[0,0]
	s_waitcnt vmcnt(2)
	v_pk_fma_f32 v[34:35], v[26:27], v[30:31], v[28:29] neg_lo:[0,0,1] neg_hi:[0,0,1]
	v_pk_fma_f32 v[26:27], v[26:27], v[30:31], v[28:29] op_sel_hi:[1,0,1]
	s_nop 0
	v_mov_b32_e32 v35, v27
	ds_write_b64 v24, v[34:35] offset:16384
	s_waitcnt vmcnt(0)
	ds_write_b64 v31, v[32:33]
	ds_write_b64 v24, v[32:33]
	v_add_u32_e32 v24, 0x1000, v24
	s_andn2_b64 exec, exec, s[6:7]
	s_cbranch_execnz .LBB0_102
	s_or_b64 exec, exec, s[6:7]
	v_readlane_b32 s0, v254, 61
	s_and_b32 s28, s0, 3
	s_cmp_gt_u32 s28, 1
	s_mov_b64 s[6:7], -1
	s_waitcnt lgkmcnt(0)
	s_barrier
	s_cbranch_scc0 .LBB0_113
	s_lshl_b64 s[6:7], s[42:43], 19
	s_cmp_lg_u32 s28, 2
	s_mov_b64 s[44:45], -1
	s_cbranch_scc0 .LBB0_108
	v_lshl_add_u64 v[22:23], v[0:1], 0, s[6:7]
	s_mov_b32 s43, 3
	s_movk_i32 s44, 0xc000
	s_mov_b32 s45, 0
	s_mov_b32 s46, 0
	s_mov_b32 s19, 0x20000

; __device__ __forceinline__ void s5_tables(const Params& P, int g, int part, unsigned char* lds) {
;     ...
;             if (j == 0) { const float dv = P.s5d[g * 16 + h];
; #pragma unroll
;                 for (int k = 0; k < 16; ++k) a[k] += (k == h) ? dv : 0.f; }
.LBB0_128:
	global_load_dword v52, v[22:23], off nt
	v_readlane_b32 s10, v254, 11
	v_readlane_b32 s11, v254, 12
	s_waitcnt vmcnt(0)
	s_nop 0
	v_cndmask_b32_e64 v53, 0, v52, s[10:11]
	v_readlane_b32 s10, v254, 13
	v_readlane_b32 s11, v254, 14
	v_add_f32_e32 v38, v38, v53
	s_nop 0
	v_cndmask_b32_e64 v54, 0, v52, s[10:11]
	v_readlane_b32 s10, v254, 15
	v_readlane_b32 s11, v254, 16
	v_add_f32_e32 v39, v39, v54
	s_nop 0
	v_cndmask_b32_e64 v55, 0, v52, s[10:11]
	v_readlane_b32 s10, v254, 17
	v_readlane_b32 s11, v254, 18
	v_add_f32_e32 v36, v36, v55
	s_nop 0
	v_cndmask_b32_e64 v56, 0, v52, s[10:11]
	v_readlane_b32 s10, v254, 19
	v_readlane_b32 s11, v254, 20
	v_add_f32_e32 v37, v37, v56
	s_nop 0
	v_cndmask_b32_e64 v58, 0, v52, s[10:11]
	v_readlane_b32 s10, v254, 21
	v_readlane_b32 s11, v254, 22
	v_add_f32_e32 v34, v34, v58
	s_nop 0
	v_cndmask_b32_e64 v59, 0, v52, s[10:11]
	v_readlane_b32 s10, v254, 23
	v_readlane_b32 s11, v254, 24
	v_add_f32_e32 v35, v35, v59
	s_nop 0
	v_cndmask_b32_e64 v60, 0, v52, s[10:11]
	v_readlane_b32 s10, v254, 25
	v_readlane_b32 s11, v254, 26
	v_add_f32_e32 v32, v32, v60
	s_nop 0
	v_cndmask_b32_e64 v61, 0, v52, s[10:11]
	v_readlane_b32 s10, v254, 27
	v_readlane_b32 s11, v254, 28
	v_add_f32_e32 v33, v33, v61
	s_nop 0
	v_cndmask_b32_e64 v62, 0, v52, s[10:11]
	v_readlane_b32 s10, v254, 29
	v_readlane_b32 s11, v254, 30
	v_add_f32_e32 v30, v30, v62
	s_nop 0
	v_cndmask_b32_e64 v63, 0, v52, s[10:11]
	v_readlane_b32 s10, v254, 31
	v_readlane_b32 s11, v254, 32
	v_add_f32_e32 v31, v31, v63
	s_nop 0
	v_cndmask_b32_e64 v64, 0, v52, s[10:11]
	v_readlane_b32 s10, v254, 55
	v_readlane_b32 s11, v254, 56
	v_add_f32_e32 v28, v28, v64
	s_nop 0
	v_cndmask_b32_e64 v65, 0, v52, s[10:11]
	v_readlane_b32 s10, v254, 57
	v_readlane_b32 s11, v254, 58
	v_add_f32_e32 v29, v29, v65
	s_nop 0
	v_cndmask_b32_e64 v66, 0, v52, s[10:11]
	v_readlane_b32 s10, v254, 62
	v_readlane_b32 s11, v254, 63
	v_add_f32_e32 v26, v26, v66
	s_nop 0
	v_cndmask_b32_e64 v67, 0, v52, s[10:11]
	v_readlane_b32 s10, v255, 0
	v_readlane_b32 s11, v255, 1
	v_add_f32_e32 v27, v27, v67
	s_nop 0
	v_cndmask_b32_e64 v68, 0, v52, s[10:11]
	v_readlane_b32 s10, v255, 2
	v_readlane_b32 s11, v255, 3
	v_add_f32_e32 v24, v24, v68
	s_nop 0
	v_cndmask_b32_e64 v52, 0, v52, s[10:11]
	v_add_f32_e32 v25, v25, v52
	s_branch .LBB0_118
